# stack: K-loop hand-off trim + serialising lgkmcnt(0) hoisted out of P2/tail K-loops + P8 tile order per XCD round changed from 8 row-tiles x 4 col-tiles to 4 x 8 (same perimeter, A re-streamed from HB
# baseline (speedup 1.0000x reference)
; #define PG8_STAGE(bufoff, gbase, voff) do { _Pragma("unroll") for (int _i = 0; _i < 2; ++_i) \
;         __builtin_amdgcn_global_load_lds((const unsigned*)((const char*)(gbase) + (voff)[_i]), (PG8_LAS unsigned*)(lds + (bufoff) + ldsw + _i * 8192), 16, 0, 0); } while (0)
; #define PG8_LDA(dst, b, h) do { _Pragma("unroll") for (int m = 0; m < 4; ++m) _Pragma("unroll") for (int k = 0; k < 2; ++k) dst[m][k] = *(const PG8_LAS bf16x8*)(lds + PG8_SA(b, h) + aoff + m * 2048 + k * 1024); } while (0)
; #define PG8_LDB(dst, b, h) do { _Pragma("unroll") for (int n = 0; n < 2; ++n) _Pragma("unroll") for (int k = 0; k < 2; ++k) dst[n][k] = *(const PG8_LAS bf16x8*)(lds + PG8_SB(b, h) + boff + n * 2048 + k * 1024); } while (0)
; #define PG8_WAIT_V(n) asm volatile("s_waitcnt vmcnt(" #n ")" ::: "memory")
; #define PG8_WAIT_L(n) asm volatile("s_waitcnt lgkmcnt(" #n ")" ::: "memory")
; #define PG8_BAR __builtin_amdgcn_s_barrier()
; #define PG8_SCHED __builtin_amdgcn_sched_barrier(0)
; template <class Epi, class Sched, bool ALIGN_EPI = false, bool SP2 = false>
; __device__ __forceinline__ void gemm_phase(PG8_LAS unsigned char* lds, const Gemm g, const Sched& S, const Epi& E) {
;     ...
;         const bool has_next = S.next(ui + 1, nxt);
;         const char* nA = has_next ? (const char*)g.A + (size_t)nxt.pm * tstep : cA; const char* nB = has_next ? (const char*)g.Bt + (size_t)nxt.pn * tstep : cB;
;         for (int t = 0; t < nt; t += 2) {
;             const bool last = (t == nt - 2);
;             const char* a1 = cA + (size_t)(t + 1) * kstep;
;             const char* a2 = last ? nA : cA + (size_t)(t + 2) * kstep; const char* b2 = last ? nB : cB + (size_t)(t + 2) * kstep;
;             const char* a3 = a2 + kstep; const char* b3 = b2 + kstep;
;             if (last && has_next) S.a_ready(nxt);
;             if constexpr (SP2) {
;             PG8_LDB(B0, 0, 0); PG8_LDB(B1, 0, 1); PG8_SCHED; PG8_LDA(At, 0, 0); PG8_STAGE(PG8_SA(1, 1), a1 + hstep, voffA);
;             PG8_WAIT_V(8); PG8_WAIT_L(0); PG8_BAR; PG8_MMA(0, 0, At, B0); PG8_MMA(0, 1, At, B1); PG8_BAR; PG8_SCHED;
;     ...
; #pragma unroll
;         for (int a = 0; a < 2; ++a)
; #pragma unroll
;             for (int b = 0; b < 2; ++b)
; #pragma unroll
;                 for (int m = 0; m < 4; ++m)
; #pragma unroll
;                     for (int n = 0; n < 2; ++n) acc[a][b][m][n] = (f32x4){0.f, 0.f, 0.f, 0.f};
.LBB0_182:
	s_ashr_i32 s39, s38, 31
	s_lshl_b64 s[10:11], s[38:39], 21
	s_add_u32 s70, s74, s10
	v_readlane_b32 s1, v247, 29
	s_addc_u32 s71, s1, s11
	s_and_b64 s[10:11], s[66:67], exec
	s_cselect_b32 s1, s71, s7
	s_cselect_b32 s12, s70, s6
	s_ashr_i32 s85, s84, 31
	s_lshl_b64 s[10:11], s[84:85], 21
	s_add_u32 s72, s36, s10
	s_addc_u32 s73, s37, s11
	s_and_b64 s[10:11], s[66:67], exec
	s_cselect_b32 s13, s73, s9
	s_cselect_b32 s14, s72, s8
	s_add_u32 s6, s6, 0x100080
	s_addc_u32 s7, s7, 0
	s_add_u32 s15, s8, 0x100
	v_mov_b32_e32 v2, 0
	s_addc_u32 s16, s9, 0
	s_mov_b32 s17, -2
	v_mov_b32_e32 v3, v2
	v_mov_b32_e32 v4, v2
	v_mov_b32_e32 v5, v2
	v_mov_b32_e32 v6, v2
	v_mov_b32_e32 v7, v2
	v_mov_b32_e32 v8, v2
	v_mov_b32_e32 v9, v2
	v_mov_b32_e32 v14, v2
	v_mov_b32_e32 v15, v2
	v_mov_b32_e32 v16, v2
	v_mov_b32_e32 v17, v2
	v_mov_b32_e32 v22, v2
	v_mov_b32_e32 v23, v2
	v_mov_b32_e32 v24, v2
	v_mov_b32_e32 v25, v2
	v_mov_b32_e32 v30, v2
	v_mov_b32_e32 v31, v2
	v_mov_b32_e32 v32, v2
	v_mov_b32_e32 v33, v2
	v_mov_b32_e32 v38, v2
	v_mov_b32_e32 v39, v2
	v_mov_b32_e32 v40, v2
	v_mov_b32_e32 v41, v2
	v_mov_b32_e32 v46, v2
	v_mov_b32_e32 v47, v2
	v_mov_b32_e32 v48, v2
	v_mov_b32_e32 v49, v2
	v_mov_b32_e32 v54, v2
	v_mov_b32_e32 v55, v2
	v_mov_b32_e32 v56, v2
	v_mov_b32_e32 v57, v2
	v_mov_b32_e32 v10, v2
	v_mov_b32_e32 v11, v2
	v_mov_b32_e32 v12, v2
	v_mov_b32_e32 v13, v2
	v_mov_b32_e32 v18, v2
	v_mov_b32_e32 v19, v2
	v_mov_b32_e32 v20, v2
	v_mov_b32_e32 v21, v2
	v_mov_b32_e32 v26, v2
	v_mov_b32_e32 v27, v2
	v_mov_b32_e32 v28, v2
	v_mov_b32_e32 v29, v2
	v_mov_b32_e32 v34, v2
	v_mov_b32_e32 v35, v2
	v_mov_b32_e32 v36, v2
	v_mov_b32_e32 v37, v2
	v_mov_b32_e32 v42, v2
	v_mov_b32_e32 v43, v2
	v_mov_b32_e32 v44, v2
	v_mov_b32_e32 v45, v2
	v_mov_b32_e32 v50, v2
	v_mov_b32_e32 v51, v2
	v_mov_b32_e32 v52, v2
	v_mov_b32_e32 v53, v2
	v_mov_b32_e32 v58, v2
	v_mov_b32_e32 v59, v2
	v_mov_b32_e32 v60, v2
	v_mov_b32_e32 v61, v2
	v_mov_b32_e32 v62, v2
	v_mov_b32_e32 v63, v2
	v_mov_b32_e32 v64, v2
	v_mov_b32_e32 v65, v2
	v_mov_b32_e32 v66, v2
	v_mov_b32_e32 v67, v2
	v_mov_b32_e32 v68, v2
	v_mov_b32_e32 v69, v2
	v_mov_b32_e32 v70, v2
	v_mov_b32_e32 v71, v2
	v_mov_b32_e32 v72, v2
	v_mov_b32_e32 v73, v2
	v_mov_b32_e32 v78, v2
	v_mov_b32_e32 v79, v2
	v_mov_b32_e32 v80, v2
	v_mov_b32_e32 v81, v2
	v_mov_b32_e32 v86, v2
	v_mov_b32_e32 v87, v2
	v_mov_b32_e32 v88, v2
	v_mov_b32_e32 v89, v2
	v_mov_b32_e32 v94, v2
	v_mov_b32_e32 v95, v2
	v_mov_b32_e32 v96, v2
	v_mov_b32_e32 v97, v2
	v_mov_b32_e32 v102, v2
	v_mov_b32_e32 v103, v2
	v_mov_b32_e32 v104, v2
	v_mov_b32_e32 v105, v2
	v_mov_b32_e32 v110, v2
	v_mov_b32_e32 v111, v2
	v_mov_b32_e32 v112, v2
	v_mov_b32_e32 v113, v2
	v_mov_b32_e32 v118, v2
	v_mov_b32_e32 v119, v2
	v_mov_b32_e32 v120, v2
	v_mov_b32_e32 v121, v2
	v_mov_b32_e32 v74, v2
	v_mov_b32_e32 v75, v2
	v_mov_b32_e32 v76, v2
	v_mov_b32_e32 v77, v2
	v_mov_b32_e32 v82, v2
	v_mov_b32_e32 v83, v2
	v_mov_b32_e32 v84, v2
	v_mov_b32_e32 v85, v2
	v_mov_b32_e32 v90, v2
	v_mov_b32_e32 v91, v2
	v_mov_b32_e32 v92, v2
	v_mov_b32_e32 v93, v2
	v_mov_b32_e32 v98, v2
	v_mov_b32_e32 v99, v2
	v_mov_b32_e32 v100, v2
	v_mov_b32_e32 v101, v2
	v_mov_b32_e32 v106, v2
	v_mov_b32_e32 v107, v2
	v_mov_b32_e32 v108, v2
	v_mov_b32_e32 v109, v2
	v_mov_b32_e32 v114, v2
	v_mov_b32_e32 v115, v2
	v_mov_b32_e32 v116, v2
	v_mov_b32_e32 v117, v2
	v_mov_b32_e32 v122, v2
	v_mov_b32_e32 v123, v2
	v_mov_b32_e32 v124, v2
	v_mov_b32_e32 v125, v2
	v_mov_b32_e32 v126, v2
	v_mov_b32_e32 v127, v2
	v_mov_b32_e32 v128, v2
	v_mov_b32_e32 v129, v2
	s_waitcnt lgkmcnt(0)
.LBB0_183:
	ds_read_b128 v[144:147], v186
	ds_read_b128 v[148:151], v186 offset:1024
	ds_read_b128 v[152:155], v186 offset:2048
	ds_read_b128 v[156:159], v186 offset:3072
	ds_read_b128 v[160:163], v187
	ds_read_b128 v[164:167], v187 offset:1024
	ds_read_b128 v[168:171], v187 offset:2048
	ds_read_b128 v[172:175], v187 offset:3072
	s_add_u32 s8, s6, 0xfff00080
	s_addc_u32 s9, s7, -1
	s_cmp_eq_u32 s17, 60
	s_cselect_b32 s11, s1, s9
	s_cselect_b32 s10, s12, s8
	s_cselect_b32 s9, s13, s16
	s_cselect_b32 s8, s14, s15
	v_lshl_add_u64 v[214:215], s[6:7], 0, v[140:141]
	s_add_i32 m0, s41, 0xc000
	ds_read_b128 v[176:179], v188
	ds_read_b128 v[190:193], v188 offset:1024
	ds_read_b128 v[194:197], v188 offset:2048
	ds_read_b128 v[198:201], v188 offset:3072
	ds_read_b128 v[202:205], v188 offset:4096
	ds_read_b128 v[206:209], v188 offset:5120
	ds_read_b128 v[210:213], v188 offset:6144
	ds_read_b128 v[218:221], v188 offset:7168
	global_load_lds_dwordx4 v[214:215], off
	v_lshl_add_u64 v[214:215], s[6:7], 0, v[142:143]
	s_add_i32 m0, s41, 0xe000
	s_nop 0
	global_load_lds_dwordx4 v[214:215], off
	s_waitcnt vmcnt(8)
	s_waitcnt lgkmcnt(0)
	s_setprio 1
	s_barrier
; #define PG8_STAGE(bufoff, gbase, voff) do { _Pragma("unroll") for (int _i = 0; _i < 2; ++_i) \
;         __builtin_amdgcn_global_load_lds((const unsigned*)((const char*)(gbase) + (voff)[_i]), (PG8_LAS unsigned*)(lds + (bufoff) + ldsw + _i * 8192), 16, 0, 0); } while (0)
; #define PG8_LDA(dst, b, h) do { _Pragma("unroll") for (int m = 0; m < 4; ++m) _Pragma("unroll") for (int k = 0; k < 2; ++k) dst[m][k] = *(const PG8_LAS bf16x8*)(lds + PG8_SA(b, h) + aoff + m * 2048 + k * 1024); } while (0)
; #define PG8_LDB(dst, b, h) do { _Pragma("unroll") for (int n = 0; n < 2; ++n) _Pragma("unroll") for (int k = 0; k < 2; ++k) dst[n][k] = *(const PG8_LAS bf16x8*)(lds + PG8_SB(b, h) + boff + n * 2048 + k * 1024); } while (0)
; #define PG8_MMA(ai, bj, At, Bt) do { __builtin_amdgcn_s_setprio(1); _Pragma("unroll") for (int m = 0; m < 4; ++m) _Pragma("unroll") for (int n = 0; n < 2; ++n) _Pragma("unroll") for (int k = 0; k < 2; ++k) \
;         acc[ai][bj][m][n] = __builtin_amdgcn_mfma_f32_16x16x32_bf16(Bt[n][k], At[m][k], acc[ai][bj][m][n], 0, 0, 0); __builtin_amdgcn_s_setprio(0); } while (0)
; #define PG8_WAIT_V(n) asm volatile("s_waitcnt vmcnt(" #n ")" ::: "memory")
; #define PG8_WAIT_L(n) asm volatile("s_waitcnt lgkmcnt(" #n ")" ::: "memory")
; #define PG8_BAR __builtin_amdgcn_s_barrier()
; #define PG8_SCHED __builtin_amdgcn_sched_barrier(0)
; template <class Epi, class Sched, bool ALIGN_EPI = false, bool SP2 = false>
; __device__ __forceinline__ void gemm_phase(PG8_LAS unsigned char* lds, const Gemm g, const Sched& S, const Epi& E) {
;     ...
;             PG8_WAIT_V(8); PG8_WAIT_L(0); PG8_BAR; PG8_MMA(0, 0, At, B0); PG8_MMA(0, 1, At, B1); PG8_BAR; PG8_SCHED;
;             PG8_LDA(At, 0, 1); PG8_STAGE(PG8_SB(0, 0), b2, voffB); PG8_STAGE(PG8_SB(0, 1), b2 + hstep, voffB); PG8_STAGE(PG8_SA(0, 0), a2, voffA);
;             PG8_WAIT_V(8); PG8_WAIT_L(0); PG8_BAR; PG8_MMA(1, 0, At, B0); PG8_MMA(1, 1, At, B1); PG8_BAR; PG8_SCHED;
;             PG8_LDB(B0, 1, 0); PG8_LDB(B1, 1, 1); PG8_SCHED; PG8_LDA(At, 1, 0); PG8_STAGE(PG8_SA(0, 1), a2 + hstep, voffA);
;             PG8_WAIT_V(8); PG8_WAIT_L(0); PG8_BAR; PG8_MMA(0, 0, At, B0); PG8_MMA(0, 1, At, B1); PG8_BAR; PG8_SCHED;
	v_mfma_f32_16x16x32_bf16 v[126:129], v[144:147], v[176:179], v[126:129]
	v_mfma_f32_16x16x32_bf16 v[122:125], v[152:155], v[176:179], v[122:125]
	v_mfma_f32_16x16x32_bf16 v[114:117], v[144:147], v[194:197], v[114:117]
	v_mfma_f32_16x16x32_bf16 v[106:109], v[152:155], v[194:197], v[106:109]
	v_mfma_f32_16x16x32_bf16 v[98:101], v[144:147], v[202:205], v[98:101]
	v_mfma_f32_16x16x32_bf16 v[90:93], v[152:155], v[202:205], v[90:93]
	v_mfma_f32_16x16x32_bf16 v[82:85], v[144:147], v[210:213], v[82:85]
	v_mfma_f32_16x16x32_bf16 v[74:77], v[152:155], v[210:213], v[74:77]
	v_mfma_f32_16x16x32_bf16 v[126:129], v[148:151], v[190:193], v[126:129]
	v_mfma_f32_16x16x32_bf16 v[122:125], v[156:159], v[190:193], v[122:125]
	v_mfma_f32_16x16x32_bf16 v[114:117], v[148:151], v[198:201], v[114:117]
	v_mfma_f32_16x16x32_bf16 v[106:109], v[156:159], v[198:201], v[106:109]
	v_mfma_f32_16x16x32_bf16 v[98:101], v[148:151], v[206:209], v[98:101]
	v_mfma_f32_16x16x32_bf16 v[90:93], v[156:159], v[206:209], v[90:93]
	v_mfma_f32_16x16x32_bf16 v[82:85], v[148:151], v[218:221], v[82:85]
	v_mfma_f32_16x16x32_bf16 v[74:77], v[156:159], v[218:221], v[74:77]
	s_setprio 0
	s_setprio 1
	v_mfma_f32_16x16x32_bf16 v[118:121], v[160:163], v[176:179], v[118:121]
	v_mfma_f32_16x16x32_bf16 v[110:113], v[168:171], v[176:179], v[110:113]
	v_mfma_f32_16x16x32_bf16 v[102:105], v[160:163], v[194:197], v[102:105]
	v_mfma_f32_16x16x32_bf16 v[94:97], v[168:171], v[194:197], v[94:97]
	v_mfma_f32_16x16x32_bf16 v[86:89], v[160:163], v[202:205], v[86:89]
	v_mfma_f32_16x16x32_bf16 v[78:81], v[168:171], v[202:205], v[78:81]
	v_mfma_f32_16x16x32_bf16 v[70:73], v[160:163], v[210:213], v[70:73]
	v_mfma_f32_16x16x32_bf16 v[66:69], v[168:171], v[210:213], v[66:69]
	v_mfma_f32_16x16x32_bf16 v[118:121], v[164:167], v[190:193], v[118:121]
	v_mfma_f32_16x16x32_bf16 v[110:113], v[172:175], v[190:193], v[110:113]
	v_mfma_f32_16x16x32_bf16 v[102:105], v[164:167], v[198:201], v[102:105]
	v_mfma_f32_16x16x32_bf16 v[94:97], v[172:175], v[198:201], v[94:97]
	v_mfma_f32_16x16x32_bf16 v[86:89], v[164:167], v[206:209], v[86:89]
	v_mfma_f32_16x16x32_bf16 v[78:81], v[172:175], v[206:209], v[78:81]
	v_mfma_f32_16x16x32_bf16 v[70:73], v[164:167], v[218:221], v[70:73]
	v_mfma_f32_16x16x32_bf16 v[66:69], v[172:175], v[218:221], v[66:69]
	s_barrier
	s_setprio 0
	s_add_i32 s18, s62, s5
	v_lshl_add_u64 v[214:215], s[8:9], 0, v[132:133]
	s_mov_b32 m0, s18
	ds_read_b128 v[176:179], v188 offset:16384
	ds_read_b128 v[190:193], v188 offset:17408
	ds_read_b128 v[194:197], v188 offset:18432
	ds_read_b128 v[198:201], v188 offset:19456
	ds_read_b128 v[202:205], v188 offset:20480
	ds_read_b128 v[206:209], v188 offset:21504
	ds_read_b128 v[210:213], v188 offset:22528
	ds_read_b128 v[218:221], v188 offset:23552
	global_load_lds_dwordx4 v[214:215], off
	s_add_i32 m0, s18, 0x2000
	s_add_u32 s18, s8, 0x100000
	v_lshl_add_u64 v[222:223], s[8:9], 0, v[136:137]
	s_addc_u32 s19, s9, 0
	s_add_i32 s20, s63, s5
	global_load_lds_dwordx4 v[222:223], off
	v_lshl_add_u64 v[224:225], s[18:19], 0, v[132:133]
	s_mov_b32 m0, s20
	v_lshl_add_u64 v[226:227], s[10:11], 0, v[134:135]
	global_load_lds_dwordx4 v[224:225], off
	v_lshl_add_u64 v[224:225], s[18:19], 0, v[136:137]
	s_add_i32 m0, s20, 0x2000
	s_nop 0
	global_load_lds_dwordx4 v[224:225], off
	v_lshl_add_u64 v[224:225], s[10:11], 0, v[130:131]
	s_mov_b32 m0, s41
	s_nop 0
	global_load_lds_dwordx4 v[224:225], off
	s_mov_b32 m0, s43
	s_nop 0
	global_load_lds_dwordx4 v[226:227], off
	s_waitcnt vmcnt(8)
	s_waitcnt lgkmcnt(0)
	s_setprio 1
	s_barrier
	v_mfma_f32_16x16x32_bf16 v[62:65], v[144:147], v[176:179], v[62:65]
	v_mfma_f32_16x16x32_bf16 v[58:61], v[152:155], v[176:179], v[58:61]
	v_mfma_f32_16x16x32_bf16 v[50:53], v[144:147], v[194:197], v[50:53]
	v_mfma_f32_16x16x32_bf16 v[42:45], v[152:155], v[194:197], v[42:45]
	v_mfma_f32_16x16x32_bf16 v[34:37], v[144:147], v[202:205], v[34:37]
	v_mfma_f32_16x16x32_bf16 v[26:29], v[152:155], v[202:205], v[26:29]
	v_mfma_f32_16x16x32_bf16 v[18:21], v[144:147], v[210:213], v[18:21]
	v_mfma_f32_16x16x32_bf16 v[10:13], v[152:155], v[210:213], v[10:13]
	v_mfma_f32_16x16x32_bf16 v[62:65], v[148:151], v[190:193], v[62:65]
	v_mfma_f32_16x16x32_bf16 v[58:61], v[156:159], v[190:193], v[58:61]
	v_mfma_f32_16x16x32_bf16 v[50:53], v[148:151], v[198:201], v[50:53]
	v_mfma_f32_16x16x32_bf16 v[42:45], v[156:159], v[198:201], v[42:45]
	v_mfma_f32_16x16x32_bf16 v[34:37], v[148:151], v[206:209], v[34:37]
	v_mfma_f32_16x16x32_bf16 v[26:29], v[156:159], v[206:209], v[26:29]
	v_mfma_f32_16x16x32_bf16 v[18:21], v[148:151], v[218:221], v[18:21]
	v_mfma_f32_16x16x32_bf16 v[10:13], v[156:159], v[218:221], v[10:13]
	s_setprio 0
	s_setprio 1
	v_mfma_f32_16x16x32_bf16 v[54:57], v[160:163], v[176:179], v[54:57]
	v_mfma_f32_16x16x32_bf16 v[46:49], v[168:171], v[176:179], v[46:49]
	v_mfma_f32_16x16x32_bf16 v[38:41], v[160:163], v[194:197], v[38:41]
	v_mfma_f32_16x16x32_bf16 v[30:33], v[168:171], v[194:197], v[30:33]
	v_mfma_f32_16x16x32_bf16 v[22:25], v[160:163], v[202:205], v[22:25]
	v_mfma_f32_16x16x32_bf16 v[14:17], v[168:171], v[202:205], v[14:17]
	v_mfma_f32_16x16x32_bf16 v[6:9], v[160:163], v[210:213], v[6:9]
	v_mfma_f32_16x16x32_bf16 v[2:5], v[168:171], v[210:213], v[2:5]
	v_mfma_f32_16x16x32_bf16 v[54:57], v[164:167], v[190:193], v[54:57]
	v_mfma_f32_16x16x32_bf16 v[46:49], v[172:175], v[190:193], v[46:49]
	v_mfma_f32_16x16x32_bf16 v[38:41], v[164:167], v[198:201], v[38:41]
	v_mfma_f32_16x16x32_bf16 v[30:33], v[172:175], v[198:201], v[30:33]
	v_mfma_f32_16x16x32_bf16 v[22:25], v[164:167], v[206:209], v[22:25]
	v_mfma_f32_16x16x32_bf16 v[14:17], v[172:175], v[206:209], v[14:17]
	v_mfma_f32_16x16x32_bf16 v[6:9], v[164:167], v[218:221], v[6:9]
	v_mfma_f32_16x16x32_bf16 v[2:5], v[172:175], v[218:221], v[2:5]
	s_barrier
; #define PG8_STAGE(bufoff, gbase, voff) do { _Pragma("unroll") for (int _i = 0; _i < 2; ++_i) \
;         __builtin_amdgcn_global_load_lds((const unsigned*)((const char*)(gbase) + (voff)[_i]), (PG8_LAS unsigned*)(lds + (bufoff) + ldsw + _i * 8192), 16, 0, 0); } while (0)
; #define PG8_LDA(dst, b, h) do { _Pragma("unroll") for (int m = 0; m < 4; ++m) _Pragma("unroll") for (int k = 0; k < 2; ++k) dst[m][k] = *(const PG8_LAS bf16x8*)(lds + PG8_SA(b, h) + aoff + m * 2048 + k * 1024); } while (0)
; #define PG8_LDB(dst, b, h) do { _Pragma("unroll") for (int n = 0; n < 2; ++n) _Pragma("unroll") for (int k = 0; k < 2; ++k) dst[n][k] = *(const PG8_LAS bf16x8*)(lds + PG8_SB(b, h) + boff + n * 2048 + k * 1024); } while (0)
; #define PG8_MMA(ai, bj, At, Bt) do { __builtin_amdgcn_s_setprio(1); _Pragma("unroll") for (int m = 0; m < 4; ++m) _Pragma("unroll") for (int n = 0; n < 2; ++n) _Pragma("unroll") for (int k = 0; k < 2; ++k) \
;         acc[ai][bj][m][n] = __builtin_amdgcn_mfma_f32_16x16x32_bf16(Bt[n][k], At[m][k], acc[ai][bj][m][n], 0, 0, 0); __builtin_amdgcn_s_setprio(0); } while (0)
; #define PG8_WAIT_V(n) asm volatile("s_waitcnt vmcnt(" #n ")" ::: "memory")
; #define PG8_WAIT_L(n) asm volatile("s_waitcnt lgkmcnt(" #n ")" ::: "memory")
; #define PG8_BAR __builtin_amdgcn_s_barrier()
; #define PG8_SCHED __builtin_amdgcn_sched_barrier(0)
; template <class Epi, class Sched, bool ALIGN_EPI = false, bool SP2 = false>
; __device__ __forceinline__ void gemm_phase(PG8_LAS unsigned char* lds, const Gemm g, const Sched& S, const Epi& E) {
;     ...
;             PG8_LDB(B0, 1, 0); PG8_LDB(B1, 1, 1); PG8_SCHED; PG8_LDA(At, 1, 0); PG8_STAGE(PG8_SA(0, 1), a2 + hstep, voffA);
;             PG8_WAIT_V(8); PG8_WAIT_L(0); PG8_BAR; PG8_MMA(0, 0, At, B0); PG8_MMA(0, 1, At, B1); PG8_BAR; PG8_SCHED;
	s_setprio 0
	s_add_i32 s18, 0, 0x18000
	v_add_u32_e32 v139, s18, v180
	s_add_i32 s19, 0, 0x1c000
	ds_read_b128 v[144:147], v139
	ds_read_b128 v[148:151], v139 offset:1024
	ds_read_b128 v[152:155], v139 offset:2048
	ds_read_b128 v[156:159], v139 offset:3072
	v_add_u32_e32 v139, s19, v180
	ds_read_b128 v[160:163], v139
	ds_read_b128 v[164:167], v139 offset:1024
	ds_read_b128 v[168:171], v139 offset:2048
	ds_read_b128 v[172:175], v139 offset:3072
	s_add_u32 s10, s10, 0x100000
	s_addc_u32 s11, s11, 0
	s_mov_b32 m0, s45
	v_lshl_add_u64 v[228:229], s[10:11], 0, v[130:131]
	ds_read_b128 v[176:179], v188 offset:32768
	ds_read_b128 v[190:193], v188 offset:33792
	ds_read_b128 v[194:197], v188 offset:34816
	ds_read_b128 v[198:201], v188 offset:35840
	ds_read_b128 v[202:205], v188 offset:36864
	ds_read_b128 v[206:209], v188 offset:37888
	ds_read_b128 v[210:213], v188 offset:38912
	ds_read_b128 v[218:221], v188 offset:39936
	global_load_lds_dwordx4 v[228:229], off
	v_lshl_add_u64 v[228:229], s[10:11], 0, v[134:135]
	s_mov_b32 m0, s47
	s_nop 0
	global_load_lds_dwordx4 v[228:229], off
	s_waitcnt vmcnt(8)
	s_waitcnt lgkmcnt(0)
	s_setprio 1
	s_barrier
	v_mfma_f32_16x16x32_bf16 v[126:129], v[144:147], v[176:179], v[126:129]
	v_mfma_f32_16x16x32_bf16 v[122:125], v[152:155], v[176:179], v[122:125]
	v_mfma_f32_16x16x32_bf16 v[114:117], v[144:147], v[194:197], v[114:117]
	v_mfma_f32_16x16x32_bf16 v[106:109], v[152:155], v[194:197], v[106:109]
	v_mfma_f32_16x16x32_bf16 v[98:101], v[144:147], v[202:205], v[98:101]
	v_mfma_f32_16x16x32_bf16 v[90:93], v[152:155], v[202:205], v[90:93]
	v_mfma_f32_16x16x32_bf16 v[82:85], v[144:147], v[210:213], v[82:85]
	v_mfma_f32_16x16x32_bf16 v[74:77], v[152:155], v[210:213], v[74:77]
	v_mfma_f32_16x16x32_bf16 v[126:129], v[148:151], v[190:193], v[126:129]
	v_mfma_f32_16x16x32_bf16 v[122:125], v[156:159], v[190:193], v[122:125]
	v_mfma_f32_16x16x32_bf16 v[114:117], v[148:151], v[198:201], v[114:117]
	v_mfma_f32_16x16x32_bf16 v[106:109], v[156:159], v[198:201], v[106:109]
	v_mfma_f32_16x16x32_bf16 v[98:101], v[148:151], v[206:209], v[98:101]
	v_mfma_f32_16x16x32_bf16 v[90:93], v[156:159], v[206:209], v[90:93]
	v_mfma_f32_16x16x32_bf16 v[82:85], v[148:151], v[218:221], v[82:85]
	v_mfma_f32_16x16x32_bf16 v[74:77], v[156:159], v[218:221], v[74:77]
	s_setprio 0
	s_setprio 1
	v_mfma_f32_16x16x32_bf16 v[118:121], v[160:163], v[176:179], v[118:121]
	v_mfma_f32_16x16x32_bf16 v[110:113], v[168:171], v[176:179], v[110:113]
	v_mfma_f32_16x16x32_bf16 v[102:105], v[160:163], v[194:197], v[102:105]
	v_mfma_f32_16x16x32_bf16 v[94:97], v[168:171], v[194:197], v[94:97]
	v_mfma_f32_16x16x32_bf16 v[86:89], v[160:163], v[202:205], v[86:89]
	v_mfma_f32_16x16x32_bf16 v[78:81], v[168:171], v[202:205], v[78:81]
	v_mfma_f32_16x16x32_bf16 v[70:73], v[160:163], v[210:213], v[70:73]
	v_mfma_f32_16x16x32_bf16 v[66:69], v[168:171], v[210:213], v[66:69]
	v_mfma_f32_16x16x32_bf16 v[118:121], v[164:167], v[190:193], v[118:121]
	v_mfma_f32_16x16x32_bf16 v[110:113], v[172:175], v[190:193], v[110:113]
	v_mfma_f32_16x16x32_bf16 v[102:105], v[164:167], v[198:201], v[102:105]
	v_mfma_f32_16x16x32_bf16 v[94:97], v[172:175], v[198:201], v[94:97]
	v_mfma_f32_16x16x32_bf16 v[86:89], v[164:167], v[206:209], v[86:89]
	v_mfma_f32_16x16x32_bf16 v[78:81], v[172:175], v[206:209], v[78:81]
	v_mfma_f32_16x16x32_bf16 v[70:73], v[164:167], v[218:221], v[70:73]
	v_mfma_f32_16x16x32_bf16 v[66:69], v[172:175], v[218:221], v[66:69]
	s_barrier
; #define PG8_STAGE(bufoff, gbase, voff) do { _Pragma("unroll") for (int _i = 0; _i < 2; ++_i) \
;         __builtin_amdgcn_global_load_lds((const unsigned*)((const char*)(gbase) + (voff)[_i]), (PG8_LAS unsigned*)(lds + (bufoff) + ldsw + _i * 8192), 16, 0, 0); } while (0)
; #define PG8_LDA(dst, b, h) do { _Pragma("unroll") for (int m = 0; m < 4; ++m) _Pragma("unroll") for (int k = 0; k < 2; ++k) dst[m][k] = *(const PG8_LAS bf16x8*)(lds + PG8_SA(b, h) + aoff + m * 2048 + k * 1024); } while (0)
; #define PG8_MMA(ai, bj, At, Bt) do { __builtin_amdgcn_s_setprio(1); _Pragma("unroll") for (int m = 0; m < 4; ++m) _Pragma("unroll") for (int n = 0; n < 2; ++n) _Pragma("unroll") for (int k = 0; k < 2; ++k) \
;         acc[ai][bj][m][n] = __builtin_amdgcn_mfma_f32_16x16x32_bf16(Bt[n][k], At[m][k], acc[ai][bj][m][n], 0, 0, 0); __builtin_amdgcn_s_setprio(0); } while (0)
; #define PG8_WAIT_V(n) asm volatile("s_waitcnt vmcnt(" #n ")" ::: "memory")
; #define PG8_WAIT_L(n) asm volatile("s_waitcnt lgkmcnt(" #n ")" ::: "memory")
; #define PG8_BAR __builtin_amdgcn_s_barrier()
; #define PG8_SCHED __builtin_amdgcn_sched_barrier(0)
;     __device__ __forceinline__ void operator()(const f32x4 (&acc)[2][2][4][2], const Unit& u, int wr, int wc, int fr, int fq) const {
;         const int pn = u.pn, row0 = u.pm * BM + wr * 64 + fr, cw = wc * 32 + 8 * fq;
;         if (pn < 4)       store_tile<0, 0>(acc, Q, 1024, row0, pn * 256 + cw, qscale, nullptr, 0, fq);
; template <class Epi, class Sched, bool ALIGN_EPI = false, bool SP2 = false>
; __device__ __forceinline__ void gemm_phase(PG8_LAS unsigned char* lds, const Gemm g, const Sched& S, const Epi& E) {
;     ...
;             PG8_LDA(At, 1, 1); PG8_STAGE(PG8_SB(1, 0), b3, voffB); PG8_STAGE(PG8_SB(1, 1), b3 + hstep, voffB); PG8_STAGE(PG8_SA(1, 0), a3, voffA);
;             PG8_WAIT_V(8); PG8_WAIT_L(0); PG8_BAR; PG8_MMA(1, 0, At, B0); PG8_MMA(1, 1, At, B1); PG8_BAR; PG8_SCHED;
	s_setprio 0
	s_add_i32 s10, s18, s5
	v_lshl_add_u64 v[214:215], v[214:215], 0, s[50:51]
	s_mov_b32 m0, s10
	ds_read_b128 v[176:179], v188 offset:49152
	ds_read_b128 v[190:193], v188 offset:50176
	ds_read_b128 v[194:197], v188 offset:51200
	ds_read_b128 v[198:201], v188 offset:52224
	ds_read_b128 v[202:205], v188 offset:53248
	ds_read_b128 v[206:209], v188 offset:54272
	ds_read_b128 v[210:213], v188 offset:55296
	ds_read_b128 v[218:221], v188 offset:56320
	global_load_lds_dwordx4 v[214:215], off
	s_add_i32 m0, s10, 0x2000
	s_add_u32 s8, s8, 0x100080
	v_lshl_add_u64 v[214:215], v[222:223], 0, s[50:51]
	s_addc_u32 s9, s9, 0
	s_add_i32 s10, s19, s5
	global_load_lds_dwordx4 v[214:215], off
	v_lshl_add_u64 v[214:215], s[8:9], 0, v[132:133]
	s_mov_b32 m0, s10
	s_nop 0
	global_load_lds_dwordx4 v[214:215], off
	v_lshl_add_u64 v[214:215], s[8:9], 0, v[136:137]
	s_add_i32 m0, s10, 0x2000
	s_nop 0
	global_load_lds_dwordx4 v[214:215], off
	v_lshl_add_u64 v[214:215], v[224:225], 0, s[50:51]
	s_mov_b32 m0, s55
	s_nop 0
	global_load_lds_dwordx4 v[214:215], off
	v_lshl_add_u64 v[214:215], v[226:227], 0, s[50:51]
	s_mov_b32 m0, s57
	s_nop 0
	global_load_lds_dwordx4 v[214:215], off
	s_waitcnt vmcnt(8)
	s_waitcnt lgkmcnt(0)
	s_setprio 1
	s_barrier
	v_mfma_f32_16x16x32_bf16 v[62:65], v[144:147], v[176:179], v[62:65]
	v_mfma_f32_16x16x32_bf16 v[58:61], v[152:155], v[176:179], v[58:61]
	v_mfma_f32_16x16x32_bf16 v[50:53], v[144:147], v[194:197], v[50:53]
	v_mfma_f32_16x16x32_bf16 v[42:45], v[152:155], v[194:197], v[42:45]
	v_mfma_f32_16x16x32_bf16 v[34:37], v[144:147], v[202:205], v[34:37]
	v_mfma_f32_16x16x32_bf16 v[26:29], v[152:155], v[202:205], v[26:29]
	v_mfma_f32_16x16x32_bf16 v[18:21], v[144:147], v[210:213], v[18:21]
	v_mfma_f32_16x16x32_bf16 v[10:13], v[152:155], v[210:213], v[10:13]
	v_mfma_f32_16x16x32_bf16 v[62:65], v[148:151], v[190:193], v[62:65]
	v_mfma_f32_16x16x32_bf16 v[58:61], v[156:159], v[190:193], v[58:61]
	v_mfma_f32_16x16x32_bf16 v[50:53], v[148:151], v[198:201], v[50:53]
	v_mfma_f32_16x16x32_bf16 v[42:45], v[156:159], v[198:201], v[42:45]
	v_mfma_f32_16x16x32_bf16 v[34:37], v[148:151], v[206:209], v[34:37]
	v_mfma_f32_16x16x32_bf16 v[26:29], v[156:159], v[206:209], v[26:29]
	v_mfma_f32_16x16x32_bf16 v[18:21], v[148:151], v[218:221], v[18:21]
	v_mfma_f32_16x16x32_bf16 v[10:13], v[156:159], v[218:221], v[10:13]
	s_setprio 0
	s_setprio 1
	v_mfma_f32_16x16x32_bf16 v[54:57], v[160:163], v[176:179], v[54:57]
	v_mfma_f32_16x16x32_bf16 v[46:49], v[168:171], v[176:179], v[46:49]
	v_mfma_f32_16x16x32_bf16 v[38:41], v[160:163], v[194:197], v[38:41]
	v_mfma_f32_16x16x32_bf16 v[30:33], v[168:171], v[194:197], v[30:33]
	v_mfma_f32_16x16x32_bf16 v[22:25], v[160:163], v[202:205], v[22:25]
	v_mfma_f32_16x16x32_bf16 v[14:17], v[168:171], v[202:205], v[14:17]
	v_mfma_f32_16x16x32_bf16 v[6:9], v[160:163], v[210:213], v[6:9]
	v_mfma_f32_16x16x32_bf16 v[2:5], v[168:171], v[210:213], v[2:5]
	v_mfma_f32_16x16x32_bf16 v[54:57], v[164:167], v[190:193], v[54:57]
	v_mfma_f32_16x16x32_bf16 v[46:49], v[172:175], v[190:193], v[46:49]
	v_mfma_f32_16x16x32_bf16 v[38:41], v[164:167], v[198:201], v[38:41]
	v_mfma_f32_16x16x32_bf16 v[30:33], v[172:175], v[198:201], v[30:33]
	v_mfma_f32_16x16x32_bf16 v[22:25], v[164:167], v[206:209], v[22:25]
	v_mfma_f32_16x16x32_bf16 v[14:17], v[172:175], v[206:209], v[14:17]
	v_mfma_f32_16x16x32_bf16 v[6:9], v[164:167], v[218:221], v[6:9]
	v_mfma_f32_16x16x32_bf16 v[2:5], v[172:175], v[218:221], v[2:5]
	s_barrier
	s_setprio 0
	s_add_i32 s17, s17, 2
	s_add_u32 s6, s6, 0x100
	s_addc_u32 s7, s7, 0
	s_add_u32 s15, s15, 0x100
	s_addc_u32 s16, s16, 0
	s_cmp_gt_u32 s17, 61
	s_cbranch_scc0 .LBB0_183
	s_and_b64 vcc, exec, s[22:23]
	s_cbranch_vccnz .LBB0_188
	v_lshl_add_u32 v144, s0, 8, v1
	s_cmp_gt_i32 s40, 3
	s_mov_b64 s[0:1], -1
	s_cbranch_scc1 .LBB0_189

; #define PG8_STAGE(bufoff, gbase, voff) do { _Pragma("unroll") for (int _i = 0; _i < 2; ++_i) \
;         __builtin_amdgcn_global_load_lds((const unsigned*)((const char*)(gbase) + (voff)[_i]), (PG8_LAS unsigned*)(lds + (bufoff) + ldsw + _i * 8192), 16, 0, 0); } while (0)
; #define PG8_LDA(dst, b, h) do { _Pragma("unroll") for (int m = 0; m < 4; ++m) _Pragma("unroll") for (int k = 0; k < 2; ++k) dst[m][k] = *(const PG8_LAS bf16x8*)(lds + PG8_SA(b, h) + aoff + m * 2048 + k * 1024); } while (0)
; #define PG8_LDB(dst, b, h) do { _Pragma("unroll") for (int n = 0; n < 2; ++n) _Pragma("unroll") for (int k = 0; k < 2; ++k) dst[n][k] = *(const PG8_LAS bf16x8*)(lds + PG8_SB(b, h) + boff + n * 2048 + k * 1024); } while (0)
; #define PG8_WAIT_V(n) asm volatile("s_waitcnt vmcnt(" #n ")" ::: "memory")
; #define PG8_WAIT_L(n) asm volatile("s_waitcnt lgkmcnt(" #n ")" ::: "memory")
; #define PG8_BAR __builtin_amdgcn_s_barrier()
; #define PG8_SCHED __builtin_amdgcn_sched_barrier(0)
; template <class Epi, class Sched, bool ALIGN_EPI = false, bool SP2 = false>
; __device__ __forceinline__ void gemm_phase(PG8_LAS unsigned char* lds, const Gemm g, const Sched& S, const Epi& E) {
;     ...
;         const bool has_next = S.next(ui + 1, nxt);
;         const char* nA = has_next ? (const char*)g.A + (size_t)nxt.pm * tstep : cA; const char* nB = has_next ? (const char*)g.Bt + (size_t)nxt.pn * tstep : cB;
;         for (int t = 0; t < nt; t += 2) {
;             const bool last = (t == nt - 2);
;             const char* a1 = cA + (size_t)(t + 1) * kstep;
;             const char* a2 = last ? nA : cA + (size_t)(t + 2) * kstep; const char* b2 = last ? nB : cB + (size_t)(t + 2) * kstep;
;             const char* a3 = a2 + kstep; const char* b3 = b2 + kstep;
;             if (last && has_next) S.a_ready(nxt);
;             if constexpr (SP2) {
;             PG8_LDB(B0, 0, 0); PG8_LDB(B1, 0, 1); PG8_SCHED; PG8_LDA(At, 0, 0); PG8_STAGE(PG8_SA(1, 1), a1 + hstep, voffA);
;             PG8_WAIT_V(8); PG8_WAIT_L(0); PG8_BAR; PG8_MMA(0, 0, At, B0); PG8_MMA(0, 1, At, B1); PG8_BAR; PG8_SCHED;
;     ...
; #pragma unroll
;         for (int a = 0; a < 2; ++a)
; #pragma unroll
;             for (int b = 0; b < 2; ++b)
; #pragma unroll
;                 for (int m = 0; m < 4; ++m)
; #pragma unroll
;                     for (int n = 0; n < 2; ++n) acc[a][b][m][n] = (f32x4){0.f, 0.f, 0.f, 0.f};
.LBB0_291:
	s_ashr_i32 s53, s52, 31
	s_lshl_b64 s[14:15], s[52:53], 21
	s_add_u32 s58, s74, s14
	v_readlane_b32 s14, v247, 29
	s_addc_u32 s59, s14, s15
	s_and_b64 s[14:15], s[56:57], exec
	s_cselect_b32 s33, s59, s39
	s_cselect_b32 s53, s58, s38
	s_ashr_i32 s51, s50, 31
	s_lshl_b64 s[14:15], s[50:51], 21
	s_add_u32 s14, s36, s14
	s_addc_u32 s15, s37, s15
	s_and_b64 s[42:43], s[56:57], exec
	s_cselect_b32 s51, s15, s41
	s_cselect_b32 s61, s14, s40
	s_add_u32 s38, s38, 0x100080
	s_addc_u32 s39, s39, 0
	s_add_u32 s68, s40, 0x100
	v_mov_b32_e32 v2, 0
	s_addc_u32 s69, s41, 0
	s_mov_b32 s71, -2
	v_mov_b32_e32 v3, v2
	v_mov_b32_e32 v4, v2
	v_mov_b32_e32 v5, v2
	v_mov_b32_e32 v6, v2
	v_mov_b32_e32 v7, v2
	v_mov_b32_e32 v8, v2
	v_mov_b32_e32 v9, v2
	v_mov_b32_e32 v10, v2
	v_mov_b32_e32 v11, v2
	v_mov_b32_e32 v12, v2
	v_mov_b32_e32 v13, v2
	v_mov_b32_e32 v18, v2
	v_mov_b32_e32 v19, v2
	v_mov_b32_e32 v20, v2
	v_mov_b32_e32 v21, v2
	v_mov_b32_e32 v26, v2
	v_mov_b32_e32 v27, v2
	v_mov_b32_e32 v28, v2
	v_mov_b32_e32 v29, v2
	v_mov_b32_e32 v34, v2
	v_mov_b32_e32 v35, v2
	v_mov_b32_e32 v36, v2
	v_mov_b32_e32 v37, v2
	v_mov_b32_e32 v42, v2
	v_mov_b32_e32 v43, v2
	v_mov_b32_e32 v44, v2
	v_mov_b32_e32 v45, v2
	v_mov_b32_e32 v50, v2
	v_mov_b32_e32 v51, v2
	v_mov_b32_e32 v52, v2
	v_mov_b32_e32 v53, v2
	v_mov_b32_e32 v14, v2
	v_mov_b32_e32 v15, v2
	v_mov_b32_e32 v16, v2
	v_mov_b32_e32 v17, v2
	v_mov_b32_e32 v22, v2
	v_mov_b32_e32 v23, v2
	v_mov_b32_e32 v24, v2
	v_mov_b32_e32 v25, v2
	v_mov_b32_e32 v30, v2
	v_mov_b32_e32 v31, v2
	v_mov_b32_e32 v32, v2
	v_mov_b32_e32 v33, v2
	v_mov_b32_e32 v38, v2
	v_mov_b32_e32 v39, v2
	v_mov_b32_e32 v40, v2
	v_mov_b32_e32 v41, v2
	v_mov_b32_e32 v46, v2
	v_mov_b32_e32 v47, v2
	v_mov_b32_e32 v48, v2
	v_mov_b32_e32 v49, v2
	v_mov_b32_e32 v54, v2
	v_mov_b32_e32 v55, v2
	v_mov_b32_e32 v56, v2
	v_mov_b32_e32 v57, v2
	v_mov_b32_e32 v58, v2
	v_mov_b32_e32 v59, v2
	v_mov_b32_e32 v60, v2
	v_mov_b32_e32 v61, v2
	v_mov_b32_e32 v62, v2
	v_mov_b32_e32 v63, v2
	v_mov_b32_e32 v64, v2
	v_mov_b32_e32 v65, v2
	v_mov_b32_e32 v66, v2
	v_mov_b32_e32 v67, v2
	v_mov_b32_e32 v68, v2
	v_mov_b32_e32 v69, v2
	v_mov_b32_e32 v70, v2
	v_mov_b32_e32 v71, v2
	v_mov_b32_e32 v72, v2
	v_mov_b32_e32 v73, v2
	v_mov_b32_e32 v74, v2
	v_mov_b32_e32 v75, v2
	v_mov_b32_e32 v76, v2
	v_mov_b32_e32 v77, v2
	v_mov_b32_e32 v82, v2
	v_mov_b32_e32 v83, v2
	v_mov_b32_e32 v84, v2
	v_mov_b32_e32 v85, v2
	v_mov_b32_e32 v90, v2
	v_mov_b32_e32 v91, v2
	v_mov_b32_e32 v92, v2
	v_mov_b32_e32 v93, v2
	v_mov_b32_e32 v98, v2
	v_mov_b32_e32 v99, v2
	v_mov_b32_e32 v100, v2
	v_mov_b32_e32 v101, v2
	v_mov_b32_e32 v106, v2
	v_mov_b32_e32 v107, v2
	v_mov_b32_e32 v108, v2
	v_mov_b32_e32 v109, v2
	v_mov_b32_e32 v114, v2
	v_mov_b32_e32 v115, v2
	v_mov_b32_e32 v116, v2
	v_mov_b32_e32 v117, v2
	v_mov_b32_e32 v78, v2
	v_mov_b32_e32 v79, v2
	v_mov_b32_e32 v80, v2
	v_mov_b32_e32 v81, v2
	v_mov_b32_e32 v86, v2
	v_mov_b32_e32 v87, v2
	v_mov_b32_e32 v88, v2
	v_mov_b32_e32 v89, v2
	v_mov_b32_e32 v94, v2
	v_mov_b32_e32 v95, v2
	v_mov_b32_e32 v96, v2
	v_mov_b32_e32 v97, v2
	v_mov_b32_e32 v102, v2
	v_mov_b32_e32 v103, v2
	v_mov_b32_e32 v104, v2
	v_mov_b32_e32 v105, v2
	v_mov_b32_e32 v110, v2
	v_mov_b32_e32 v111, v2
	v_mov_b32_e32 v112, v2
	v_mov_b32_e32 v113, v2
	v_mov_b32_e32 v118, v2
	v_mov_b32_e32 v119, v2
	v_mov_b32_e32 v120, v2
	v_mov_b32_e32 v121, v2
	v_mov_b32_e32 v122, v2
	v_mov_b32_e32 v123, v2
	v_mov_b32_e32 v124, v2
	v_mov_b32_e32 v125, v2
	v_mov_b32_e32 v126, v2
	v_mov_b32_e32 v127, v2
	v_mov_b32_e32 v128, v2
	v_mov_b32_e32 v129, v2
	s_waitcnt lgkmcnt(0)
.LBB0_292:
	ds_read_b128 v[146:149], v164
	ds_read_b128 v[150:153], v164 offset:1024
	ds_read_b128 v[154:157], v164 offset:2048
	ds_read_b128 v[168:171], v164 offset:3072
	ds_read_b128 v[172:175], v165
	ds_read_b128 v[176:179], v165 offset:1024
	ds_read_b128 v[180:183], v165 offset:2048
	ds_read_b128 v[184:187], v165 offset:3072
	s_add_u32 s40, s38, 0xfff00080
	s_addc_u32 s41, s39, -1
	s_cmp_eq_u32 s71, 60
	s_cselect_b32 s43, s33, s41
	s_cselect_b32 s42, s53, s40
	s_cselect_b32 s41, s51, s69
	s_cselect_b32 s40, s61, s68
	v_lshl_add_u64 v[222:223], s[38:39], 0, v[142:143]
	s_add_i32 m0, s19, 0xc000
	ds_read_b128 v[188:191], v166
	ds_read_b128 v[192:195], v166 offset:1024
	ds_read_b128 v[196:199], v166 offset:2048
	ds_read_b128 v[200:203], v166 offset:3072
	ds_read_b128 v[204:207], v166 offset:4096
	ds_read_b128 v[208:211], v166 offset:5120
	ds_read_b128 v[212:215], v166 offset:6144
	ds_read_b128 v[218:221], v166 offset:7168
	global_load_lds_dwordx4 v[222:223], off
	v_lshl_add_u64 v[222:223], s[38:39], 0, v[144:145]
	s_add_i32 m0, s19, 0xe000
	s_nop 0
	global_load_lds_dwordx4 v[222:223], off
	s_waitcnt vmcnt(8)
	s_waitcnt lgkmcnt(0)
	s_setprio 1
	s_barrier
; #define PG8_STAGE(bufoff, gbase, voff) do { _Pragma("unroll") for (int _i = 0; _i < 2; ++_i) \
;         __builtin_amdgcn_global_load_lds((const unsigned*)((const char*)(gbase) + (voff)[_i]), (PG8_LAS unsigned*)(lds + (bufoff) + ldsw + _i * 8192), 16, 0, 0); } while (0)
; #define PG8_LDA(dst, b, h) do { _Pragma("unroll") for (int m = 0; m < 4; ++m) _Pragma("unroll") for (int k = 0; k < 2; ++k) dst[m][k] = *(const PG8_LAS bf16x8*)(lds + PG8_SA(b, h) + aoff + m * 2048 + k * 1024); } while (0)
; #define PG8_LDB(dst, b, h) do { _Pragma("unroll") for (int n = 0; n < 2; ++n) _Pragma("unroll") for (int k = 0; k < 2; ++k) dst[n][k] = *(const PG8_LAS bf16x8*)(lds + PG8_SB(b, h) + boff + n * 2048 + k * 1024); } while (0)
; #define PG8_MMA(ai, bj, At, Bt) do { __builtin_amdgcn_s_setprio(1); _Pragma("unroll") for (int m = 0; m < 4; ++m) _Pragma("unroll") for (int n = 0; n < 2; ++n) _Pragma("unroll") for (int k = 0; k < 2; ++k) \
;         acc[ai][bj][m][n] = __builtin_amdgcn_mfma_f32_16x16x32_bf16(Bt[n][k], At[m][k], acc[ai][bj][m][n], 0, 0, 0); __builtin_amdgcn_s_setprio(0); } while (0)
; #define PG8_WAIT_V(n) asm volatile("s_waitcnt vmcnt(" #n ")" ::: "memory")
; #define PG8_WAIT_L(n) asm volatile("s_waitcnt lgkmcnt(" #n ")" ::: "memory")
; #define PG8_BAR __builtin_amdgcn_s_barrier()
; #define PG8_SCHED __builtin_amdgcn_sched_barrier(0)
; template <class Epi, class Sched, bool ALIGN_EPI = false, bool SP2 = false>
; __device__ __forceinline__ void gemm_phase(PG8_LAS unsigned char* lds, const Gemm g, const Sched& S, const Epi& E) {
;     ...
;             PG8_WAIT_V(8); PG8_WAIT_L(0); PG8_BAR; PG8_MMA(0, 0, At, B0); PG8_MMA(0, 1, At, B1); PG8_BAR; PG8_SCHED;
;             PG8_LDA(At, 0, 1); PG8_STAGE(PG8_SB(0, 0), b2, voffB); PG8_STAGE(PG8_SB(0, 1), b2 + hstep, voffB); PG8_STAGE(PG8_SA(0, 0), a2, voffA);
;             PG8_WAIT_V(8); PG8_WAIT_L(0); PG8_BAR; PG8_MMA(1, 0, At, B0); PG8_MMA(1, 1, At, B1); PG8_BAR; PG8_SCHED;
;             PG8_LDB(B0, 1, 0); PG8_LDB(B1, 1, 1); PG8_SCHED; PG8_LDA(At, 1, 0); PG8_STAGE(PG8_SA(0, 1), a2 + hstep, voffA);
;             PG8_WAIT_V(8); PG8_WAIT_L(0); PG8_BAR; PG8_MMA(0, 0, At, B0); PG8_MMA(0, 1, At, B1); PG8_BAR; PG8_SCHED;
	v_mfma_f32_16x16x32_bf16 v[126:129], v[146:149], v[188:191], v[126:129]
	v_mfma_f32_16x16x32_bf16 v[122:125], v[154:157], v[188:191], v[122:125]
	v_mfma_f32_16x16x32_bf16 v[118:121], v[146:149], v[196:199], v[118:121]
	v_mfma_f32_16x16x32_bf16 v[110:113], v[154:157], v[196:199], v[110:113]
	v_mfma_f32_16x16x32_bf16 v[102:105], v[146:149], v[204:207], v[102:105]
	v_mfma_f32_16x16x32_bf16 v[94:97], v[154:157], v[204:207], v[94:97]
	v_mfma_f32_16x16x32_bf16 v[86:89], v[146:149], v[212:215], v[86:89]
	v_mfma_f32_16x16x32_bf16 v[78:81], v[154:157], v[212:215], v[78:81]
	v_mfma_f32_16x16x32_bf16 v[126:129], v[150:153], v[192:195], v[126:129]
	v_mfma_f32_16x16x32_bf16 v[122:125], v[168:171], v[192:195], v[122:125]
	v_mfma_f32_16x16x32_bf16 v[118:121], v[150:153], v[200:203], v[118:121]
	v_mfma_f32_16x16x32_bf16 v[110:113], v[168:171], v[200:203], v[110:113]
	v_mfma_f32_16x16x32_bf16 v[102:105], v[150:153], v[208:211], v[102:105]
	v_mfma_f32_16x16x32_bf16 v[94:97], v[168:171], v[208:211], v[94:97]
	v_mfma_f32_16x16x32_bf16 v[86:89], v[150:153], v[218:221], v[86:89]
	v_mfma_f32_16x16x32_bf16 v[78:81], v[168:171], v[218:221], v[78:81]
	s_setprio 0
	s_setprio 1
	v_mfma_f32_16x16x32_bf16 v[114:117], v[172:175], v[188:191], v[114:117]
	v_mfma_f32_16x16x32_bf16 v[106:109], v[180:183], v[188:191], v[106:109]
	v_mfma_f32_16x16x32_bf16 v[98:101], v[172:175], v[196:199], v[98:101]
	v_mfma_f32_16x16x32_bf16 v[90:93], v[180:183], v[196:199], v[90:93]
	v_mfma_f32_16x16x32_bf16 v[82:85], v[172:175], v[204:207], v[82:85]
	v_mfma_f32_16x16x32_bf16 v[74:77], v[180:183], v[204:207], v[74:77]
	v_mfma_f32_16x16x32_bf16 v[70:73], v[172:175], v[212:215], v[70:73]
	v_mfma_f32_16x16x32_bf16 v[66:69], v[180:183], v[212:215], v[66:69]
	v_mfma_f32_16x16x32_bf16 v[114:117], v[176:179], v[192:195], v[114:117]
	v_mfma_f32_16x16x32_bf16 v[106:109], v[184:187], v[192:195], v[106:109]
	v_mfma_f32_16x16x32_bf16 v[98:101], v[176:179], v[200:203], v[98:101]
	v_mfma_f32_16x16x32_bf16 v[90:93], v[184:187], v[200:203], v[90:93]
	v_mfma_f32_16x16x32_bf16 v[82:85], v[176:179], v[208:211], v[82:85]
	v_mfma_f32_16x16x32_bf16 v[74:77], v[184:187], v[208:211], v[74:77]
	v_mfma_f32_16x16x32_bf16 v[70:73], v[176:179], v[218:221], v[70:73]
	v_mfma_f32_16x16x32_bf16 v[66:69], v[184:187], v[218:221], v[66:69]
	s_barrier
	s_setprio 0
	s_add_i32 s72, s45, s17
	v_lshl_add_u64 v[222:223], s[40:41], 0, v[132:133]
	s_mov_b32 m0, s72
	ds_read_b128 v[188:191], v166 offset:16384
	ds_read_b128 v[192:195], v166 offset:17408
	ds_read_b128 v[196:199], v166 offset:18432
	ds_read_b128 v[200:203], v166 offset:19456
	ds_read_b128 v[204:207], v166 offset:20480
	ds_read_b128 v[208:211], v166 offset:21504
	ds_read_b128 v[212:215], v166 offset:22528
	ds_read_b128 v[218:221], v166 offset:23552
	global_load_lds_dwordx4 v[222:223], off
	s_add_i32 m0, s72, 0x2000
	s_add_u32 s72, s40, 0x100000
	v_lshl_add_u64 v[224:225], s[40:41], 0, v[136:137]
	s_addc_u32 s73, s41, 0
	s_add_i32 s74, s55, s17
	global_load_lds_dwordx4 v[224:225], off
	v_lshl_add_u64 v[226:227], s[72:73], 0, v[132:133]
	s_mov_b32 m0, s74
	v_lshl_add_u64 v[228:229], s[42:43], 0, v[134:135]
	global_load_lds_dwordx4 v[226:227], off
	v_lshl_add_u64 v[226:227], s[72:73], 0, v[136:137]
	s_add_i32 m0, s74, 0x2000
	s_nop 0
	global_load_lds_dwordx4 v[226:227], off
	v_lshl_add_u64 v[226:227], s[42:43], 0, v[130:131]
	s_mov_b32 m0, s19
	s_nop 0
	global_load_lds_dwordx4 v[226:227], off
	s_mov_b32 m0, s21
	s_nop 0
	global_load_lds_dwordx4 v[228:229], off
	s_waitcnt vmcnt(8)
	s_waitcnt lgkmcnt(0)
	s_setprio 1
	s_barrier
	v_mfma_f32_16x16x32_bf16 v[62:65], v[146:149], v[188:191], v[62:65]
	v_mfma_f32_16x16x32_bf16 v[58:61], v[154:157], v[188:191], v[58:61]
	v_mfma_f32_16x16x32_bf16 v[54:57], v[146:149], v[196:199], v[54:57]
	v_mfma_f32_16x16x32_bf16 v[46:49], v[154:157], v[196:199], v[46:49]
	v_mfma_f32_16x16x32_bf16 v[38:41], v[146:149], v[204:207], v[38:41]
	v_mfma_f32_16x16x32_bf16 v[30:33], v[154:157], v[204:207], v[30:33]
	v_mfma_f32_16x16x32_bf16 v[22:25], v[146:149], v[212:215], v[22:25]
	v_mfma_f32_16x16x32_bf16 v[14:17], v[154:157], v[212:215], v[14:17]
	v_mfma_f32_16x16x32_bf16 v[62:65], v[150:153], v[192:195], v[62:65]
	v_mfma_f32_16x16x32_bf16 v[58:61], v[168:171], v[192:195], v[58:61]
	v_mfma_f32_16x16x32_bf16 v[54:57], v[150:153], v[200:203], v[54:57]
	v_mfma_f32_16x16x32_bf16 v[46:49], v[168:171], v[200:203], v[46:49]
	v_mfma_f32_16x16x32_bf16 v[38:41], v[150:153], v[208:211], v[38:41]
	v_mfma_f32_16x16x32_bf16 v[30:33], v[168:171], v[208:211], v[30:33]
	v_mfma_f32_16x16x32_bf16 v[22:25], v[150:153], v[218:221], v[22:25]
	v_mfma_f32_16x16x32_bf16 v[14:17], v[168:171], v[218:221], v[14:17]
	s_setprio 0
	s_setprio 1
	v_mfma_f32_16x16x32_bf16 v[50:53], v[172:175], v[188:191], v[50:53]
	v_mfma_f32_16x16x32_bf16 v[42:45], v[180:183], v[188:191], v[42:45]
	v_mfma_f32_16x16x32_bf16 v[34:37], v[172:175], v[196:199], v[34:37]
	v_mfma_f32_16x16x32_bf16 v[26:29], v[180:183], v[196:199], v[26:29]
	v_mfma_f32_16x16x32_bf16 v[18:21], v[172:175], v[204:207], v[18:21]
	v_mfma_f32_16x16x32_bf16 v[10:13], v[180:183], v[204:207], v[10:13]
	v_mfma_f32_16x16x32_bf16 v[6:9], v[172:175], v[212:215], v[6:9]
	v_mfma_f32_16x16x32_bf16 v[2:5], v[180:183], v[212:215], v[2:5]
	v_mfma_f32_16x16x32_bf16 v[50:53], v[176:179], v[192:195], v[50:53]
	v_mfma_f32_16x16x32_bf16 v[42:45], v[184:187], v[192:195], v[42:45]
	v_mfma_f32_16x16x32_bf16 v[34:37], v[176:179], v[200:203], v[34:37]
	v_mfma_f32_16x16x32_bf16 v[26:29], v[184:187], v[200:203], v[26:29]
	v_mfma_f32_16x16x32_bf16 v[18:21], v[176:179], v[208:211], v[18:21]
	v_mfma_f32_16x16x32_bf16 v[10:13], v[184:187], v[208:211], v[10:13]
	v_mfma_f32_16x16x32_bf16 v[6:9], v[176:179], v[218:221], v[6:9]
	v_mfma_f32_16x16x32_bf16 v[2:5], v[184:187], v[218:221], v[2:5]
	s_barrier
; #define PG8_STAGE(bufoff, gbase, voff) do { _Pragma("unroll") for (int _i = 0; _i < 2; ++_i) \
;         __builtin_amdgcn_global_load_lds((const unsigned*)((const char*)(gbase) + (voff)[_i]), (PG8_LAS unsigned*)(lds + (bufoff) + ldsw + _i * 8192), 16, 0, 0); } while (0)
; #define PG8_LDA(dst, b, h) do { _Pragma("unroll") for (int m = 0; m < 4; ++m) _Pragma("unroll") for (int k = 0; k < 2; ++k) dst[m][k] = *(const PG8_LAS bf16x8*)(lds + PG8_SA(b, h) + aoff + m * 2048 + k * 1024); } while (0)
; #define PG8_LDB(dst, b, h) do { _Pragma("unroll") for (int n = 0; n < 2; ++n) _Pragma("unroll") for (int k = 0; k < 2; ++k) dst[n][k] = *(const PG8_LAS bf16x8*)(lds + PG8_SB(b, h) + boff + n * 2048 + k * 1024); } while (0)
; #define PG8_MMA(ai, bj, At, Bt) do { __builtin_amdgcn_s_setprio(1); _Pragma("unroll") for (int m = 0; m < 4; ++m) _Pragma("unroll") for (int n = 0; n < 2; ++n) _Pragma("unroll") for (int k = 0; k < 2; ++k) \
;         acc[ai][bj][m][n] = __builtin_amdgcn_mfma_f32_16x16x32_bf16(Bt[n][k], At[m][k], acc[ai][bj][m][n], 0, 0, 0); __builtin_amdgcn_s_setprio(0); } while (0)
; #define PG8_WAIT_V(n) asm volatile("s_waitcnt vmcnt(" #n ")" ::: "memory")
; #define PG8_WAIT_L(n) asm volatile("s_waitcnt lgkmcnt(" #n ")" ::: "memory")
; #define PG8_BAR __builtin_amdgcn_s_barrier()
; #define PG8_SCHED __builtin_amdgcn_sched_barrier(0)
; template <class Epi, class Sched, bool ALIGN_EPI = false, bool SP2 = false>
; __device__ __forceinline__ void gemm_phase(PG8_LAS unsigned char* lds, const Gemm g, const Sched& S, const Epi& E) {
;     ...
;             PG8_LDB(B0, 1, 0); PG8_LDB(B1, 1, 1); PG8_SCHED; PG8_LDA(At, 1, 0); PG8_STAGE(PG8_SA(0, 1), a2 + hstep, voffA);
;             PG8_WAIT_V(8); PG8_WAIT_L(0); PG8_BAR; PG8_MMA(0, 0, At, B0); PG8_MMA(0, 1, At, B1); PG8_BAR; PG8_SCHED;
	s_setprio 0
	s_add_i32 s72, 0, 0x18000
	v_add_u32_e32 v139, s72, v158
	s_add_i32 s73, 0, 0x1c000
	ds_read_b128 v[146:149], v139
	ds_read_b128 v[150:153], v139 offset:1024
	ds_read_b128 v[154:157], v139 offset:2048
	ds_read_b128 v[168:171], v139 offset:3072
	v_add_u32_e32 v139, s73, v158
	ds_read_b128 v[172:175], v139
	ds_read_b128 v[176:179], v139 offset:1024
	ds_read_b128 v[180:183], v139 offset:2048
	ds_read_b128 v[184:187], v139 offset:3072
	s_add_u32 s42, s42, 0x100000
	s_addc_u32 s43, s43, 0
	s_mov_b32 m0, s23
	v_lshl_add_u64 v[230:231], s[42:43], 0, v[130:131]
	ds_read_b128 v[188:191], v166 offset:32768
	ds_read_b128 v[192:195], v166 offset:33792
	ds_read_b128 v[196:199], v166 offset:34816
	ds_read_b128 v[200:203], v166 offset:35840
	ds_read_b128 v[204:207], v166 offset:36864
	ds_read_b128 v[208:211], v166 offset:37888
	ds_read_b128 v[212:215], v166 offset:38912
	ds_read_b128 v[218:221], v166 offset:39936
	global_load_lds_dwordx4 v[230:231], off
	v_lshl_add_u64 v[230:231], s[42:43], 0, v[134:135]
	s_mov_b32 m0, s25
	s_nop 0
	global_load_lds_dwordx4 v[230:231], off
	s_waitcnt vmcnt(8)
	s_waitcnt lgkmcnt(0)
	s_setprio 1
	s_barrier
	v_mfma_f32_16x16x32_bf16 v[126:129], v[146:149], v[188:191], v[126:129]
	v_mfma_f32_16x16x32_bf16 v[122:125], v[154:157], v[188:191], v[122:125]
	v_mfma_f32_16x16x32_bf16 v[118:121], v[146:149], v[196:199], v[118:121]
	v_mfma_f32_16x16x32_bf16 v[110:113], v[154:157], v[196:199], v[110:113]
	v_mfma_f32_16x16x32_bf16 v[102:105], v[146:149], v[204:207], v[102:105]
	v_mfma_f32_16x16x32_bf16 v[94:97], v[154:157], v[204:207], v[94:97]
	v_mfma_f32_16x16x32_bf16 v[86:89], v[146:149], v[212:215], v[86:89]
	v_mfma_f32_16x16x32_bf16 v[78:81], v[154:157], v[212:215], v[78:81]
	v_mfma_f32_16x16x32_bf16 v[126:129], v[150:153], v[192:195], v[126:129]
	v_mfma_f32_16x16x32_bf16 v[122:125], v[168:171], v[192:195], v[122:125]
	v_mfma_f32_16x16x32_bf16 v[118:121], v[150:153], v[200:203], v[118:121]
	v_mfma_f32_16x16x32_bf16 v[110:113], v[168:171], v[200:203], v[110:113]
	v_mfma_f32_16x16x32_bf16 v[102:105], v[150:153], v[208:211], v[102:105]
	v_mfma_f32_16x16x32_bf16 v[94:97], v[168:171], v[208:211], v[94:97]
	v_mfma_f32_16x16x32_bf16 v[86:89], v[150:153], v[218:221], v[86:89]
	v_mfma_f32_16x16x32_bf16 v[78:81], v[168:171], v[218:221], v[78:81]
	s_setprio 0
	s_setprio 1
	v_mfma_f32_16x16x32_bf16 v[114:117], v[172:175], v[188:191], v[114:117]
	v_mfma_f32_16x16x32_bf16 v[106:109], v[180:183], v[188:191], v[106:109]
	v_mfma_f32_16x16x32_bf16 v[98:101], v[172:175], v[196:199], v[98:101]
	v_mfma_f32_16x16x32_bf16 v[90:93], v[180:183], v[196:199], v[90:93]
	v_mfma_f32_16x16x32_bf16 v[82:85], v[172:175], v[204:207], v[82:85]
	v_mfma_f32_16x16x32_bf16 v[74:77], v[180:183], v[204:207], v[74:77]
	v_mfma_f32_16x16x32_bf16 v[70:73], v[172:175], v[212:215], v[70:73]
	v_mfma_f32_16x16x32_bf16 v[66:69], v[180:183], v[212:215], v[66:69]
	v_mfma_f32_16x16x32_bf16 v[114:117], v[176:179], v[192:195], v[114:117]
	v_mfma_f32_16x16x32_bf16 v[106:109], v[184:187], v[192:195], v[106:109]
	v_mfma_f32_16x16x32_bf16 v[98:101], v[176:179], v[200:203], v[98:101]
	v_mfma_f32_16x16x32_bf16 v[90:93], v[184:187], v[200:203], v[90:93]
	v_mfma_f32_16x16x32_bf16 v[82:85], v[176:179], v[208:211], v[82:85]
	v_mfma_f32_16x16x32_bf16 v[74:77], v[184:187], v[208:211], v[74:77]
	v_mfma_f32_16x16x32_bf16 v[70:73], v[176:179], v[218:221], v[70:73]
	v_mfma_f32_16x16x32_bf16 v[66:69], v[184:187], v[218:221], v[66:69]
	s_barrier
; #define PG8_STAGE(bufoff, gbase, voff) do { _Pragma("unroll") for (int _i = 0; _i < 2; ++_i) \
;         __builtin_amdgcn_global_load_lds((const unsigned*)((const char*)(gbase) + (voff)[_i]), (PG8_LAS unsigned*)(lds + (bufoff) + ldsw + _i * 8192), 16, 0, 0); } while (0)
; #define PG8_LDA(dst, b, h) do { _Pragma("unroll") for (int m = 0; m < 4; ++m) _Pragma("unroll") for (int k = 0; k < 2; ++k) dst[m][k] = *(const PG8_LAS bf16x8*)(lds + PG8_SA(b, h) + aoff + m * 2048 + k * 1024); } while (0)
; #define PG8_MMA(ai, bj, At, Bt) do { __builtin_amdgcn_s_setprio(1); _Pragma("unroll") for (int m = 0; m < 4; ++m) _Pragma("unroll") for (int n = 0; n < 2; ++n) _Pragma("unroll") for (int k = 0; k < 2; ++k) \
;         acc[ai][bj][m][n] = __builtin_amdgcn_mfma_f32_16x16x32_bf16(Bt[n][k], At[m][k], acc[ai][bj][m][n], 0, 0, 0); __builtin_amdgcn_s_setprio(0); } while (0)
; #define PG8_WAIT_V(n) asm volatile("s_waitcnt vmcnt(" #n ")" ::: "memory")
; #define PG8_WAIT_L(n) asm volatile("s_waitcnt lgkmcnt(" #n ")" ::: "memory")
; #define PG8_BAR __builtin_amdgcn_s_barrier()
; #define PG8_SCHED __builtin_amdgcn_sched_barrier(0)
;     __device__ __forceinline__ void operator()(const f32x4 (&acc)[2][2][4][2], const Unit& u, int wr, int wc, int fr, int fq) const {
;         const int pn = u.pn, row0 = u.pm * BM + wr * 64 + fr, cw = wc * 32 + 8 * fq;
;         if (pn < 4)       store_tile<0, 0>(acc, Q, 1024, row0, pn * 256 + cw, qscale, nullptr, 0, fq);
;         else if (pn < 8)  store_tile<0, 0>(acc, Kb, 1024, row0, (pn - 4) * 256 + cw, 1.0f, nullptr, 0, fq);
; template <class Epi, class Sched, bool ALIGN_EPI = false, bool SP2 = false>
; __device__ __forceinline__ void gemm_phase(PG8_LAS unsigned char* lds, const Gemm g, const Sched& S, const Epi& E) {
;     ...
;             PG8_LDA(At, 1, 1); PG8_STAGE(PG8_SB(1, 0), b3, voffB); PG8_STAGE(PG8_SB(1, 1), b3 + hstep, voffB); PG8_STAGE(PG8_SA(1, 0), a3, voffA);
;             PG8_WAIT_V(8); PG8_WAIT_L(0); PG8_BAR; PG8_MMA(1, 0, At, B0); PG8_MMA(1, 1, At, B1); PG8_BAR; PG8_SCHED;
	s_setprio 0
	s_add_i32 s42, s72, s17
	v_lshl_add_u64 v[222:223], v[222:223], 0, s[10:11]
	s_mov_b32 m0, s42
	ds_read_b128 v[188:191], v166 offset:49152
	ds_read_b128 v[192:195], v166 offset:50176
	ds_read_b128 v[196:199], v166 offset:51200
	ds_read_b128 v[200:203], v166 offset:52224
	ds_read_b128 v[204:207], v166 offset:53248
	ds_read_b128 v[208:211], v166 offset:54272
	ds_read_b128 v[212:215], v166 offset:55296
	ds_read_b128 v[218:221], v166 offset:56320
	global_load_lds_dwordx4 v[222:223], off
	s_add_i32 m0, s42, 0x2000
	s_add_u32 s40, s40, 0x100080
	v_lshl_add_u64 v[222:223], v[224:225], 0, s[10:11]
	s_addc_u32 s41, s41, 0
	s_add_i32 s42, s73, s17
	global_load_lds_dwordx4 v[222:223], off
	v_lshl_add_u64 v[222:223], s[40:41], 0, v[132:133]
	s_mov_b32 m0, s42
	s_nop 0
	global_load_lds_dwordx4 v[222:223], off
	v_lshl_add_u64 v[222:223], s[40:41], 0, v[136:137]
	s_add_i32 m0, s42, 0x2000
	s_nop 0
	global_load_lds_dwordx4 v[222:223], off
	v_lshl_add_u64 v[222:223], v[226:227], 0, s[10:11]
	s_mov_b32 m0, s27
	s_nop 0
	global_load_lds_dwordx4 v[222:223], off
	v_lshl_add_u64 v[222:223], v[228:229], 0, s[10:11]
	s_mov_b32 m0, s29
	s_nop 0
	global_load_lds_dwordx4 v[222:223], off
	s_waitcnt vmcnt(8)
	s_waitcnt lgkmcnt(0)
	s_setprio 1
	s_barrier
	v_mfma_f32_16x16x32_bf16 v[62:65], v[146:149], v[188:191], v[62:65]
	v_mfma_f32_16x16x32_bf16 v[58:61], v[154:157], v[188:191], v[58:61]
	v_mfma_f32_16x16x32_bf16 v[54:57], v[146:149], v[196:199], v[54:57]
	v_mfma_f32_16x16x32_bf16 v[46:49], v[154:157], v[196:199], v[46:49]
	v_mfma_f32_16x16x32_bf16 v[38:41], v[146:149], v[204:207], v[38:41]
	v_mfma_f32_16x16x32_bf16 v[30:33], v[154:157], v[204:207], v[30:33]
	v_mfma_f32_16x16x32_bf16 v[22:25], v[146:149], v[212:215], v[22:25]
	v_mfma_f32_16x16x32_bf16 v[14:17], v[154:157], v[212:215], v[14:17]
	v_mfma_f32_16x16x32_bf16 v[62:65], v[150:153], v[192:195], v[62:65]
	v_mfma_f32_16x16x32_bf16 v[58:61], v[168:171], v[192:195], v[58:61]
	v_mfma_f32_16x16x32_bf16 v[54:57], v[150:153], v[200:203], v[54:57]
	v_mfma_f32_16x16x32_bf16 v[46:49], v[168:171], v[200:203], v[46:49]
	v_mfma_f32_16x16x32_bf16 v[38:41], v[150:153], v[208:211], v[38:41]
	v_mfma_f32_16x16x32_bf16 v[30:33], v[168:171], v[208:211], v[30:33]
	v_mfma_f32_16x16x32_bf16 v[22:25], v[150:153], v[218:221], v[22:25]
	v_mfma_f32_16x16x32_bf16 v[14:17], v[168:171], v[218:221], v[14:17]
	s_setprio 0
	s_setprio 1
	v_mfma_f32_16x16x32_bf16 v[50:53], v[172:175], v[188:191], v[50:53]
	v_mfma_f32_16x16x32_bf16 v[42:45], v[180:183], v[188:191], v[42:45]
	v_mfma_f32_16x16x32_bf16 v[34:37], v[172:175], v[196:199], v[34:37]
	v_mfma_f32_16x16x32_bf16 v[26:29], v[180:183], v[196:199], v[26:29]
	v_mfma_f32_16x16x32_bf16 v[18:21], v[172:175], v[204:207], v[18:21]
	v_mfma_f32_16x16x32_bf16 v[10:13], v[180:183], v[204:207], v[10:13]
	v_mfma_f32_16x16x32_bf16 v[6:9], v[172:175], v[212:215], v[6:9]
	v_mfma_f32_16x16x32_bf16 v[2:5], v[180:183], v[212:215], v[2:5]
	v_mfma_f32_16x16x32_bf16 v[50:53], v[176:179], v[192:195], v[50:53]
	v_mfma_f32_16x16x32_bf16 v[42:45], v[184:187], v[192:195], v[42:45]
	v_mfma_f32_16x16x32_bf16 v[34:37], v[176:179], v[200:203], v[34:37]
	v_mfma_f32_16x16x32_bf16 v[26:29], v[184:187], v[200:203], v[26:29]
	v_mfma_f32_16x16x32_bf16 v[18:21], v[176:179], v[208:211], v[18:21]
	v_mfma_f32_16x16x32_bf16 v[10:13], v[184:187], v[208:211], v[10:13]
	v_mfma_f32_16x16x32_bf16 v[6:9], v[176:179], v[218:221], v[6:9]
	v_mfma_f32_16x16x32_bf16 v[2:5], v[184:187], v[218:221], v[2:5]
	s_barrier
	s_setprio 0
	s_add_i32 s71, s71, 2
	s_add_u32 s38, s38, 0x100
	s_addc_u32 s39, s39, 0
	s_add_u32 s68, s68, 0x100
	s_addc_u32 s69, s69, 0
	s_cmp_gt_u32 s71, 61
	s_cbranch_scc0 .LBB0_292
	s_and_b64 vcc, exec, s[12:13]
	s_cbranch_vccnz .LBB0_300
	v_lshl_add_u32 v146, s0, 8, v1
	s_cmp_gt_u32 s54, 7
	s_mov_b64 s[38:39], -1
	s_cbranch_scc1 .LBB0_301

;     __host__ __device__ bool next(int i, Unit& u) const {
;         const long L = (long)i * G + c; if (L >= nwg) return false;
;         int wgid = (int)L; { const int q = nwg / NXCD, r = nwg % NXCD, xcd = wgid % NXCD, off = wgid / NXCD; wgid = (xcd < r ? xcd * (q + 1) : r * (q + 1) + (xcd - r) * q) + off; }
;         const int nig = WGM * nN, gid = wgid / nig, fm = gid * WGM, gsz = (nM - fm) < WGM ? (nM - fm) : WGM;
;         u.pm = fm + ((wgid % nig) % gsz); u.pn = (wgid % nig) / gsz; return true;
.LBB0_1075:
	s_add_i32 s0, s7, s0
	s_ashr_i32 s1, s0, 31
	s_lshr_b32 s1, s1, 25
	s_add_i32 s1, s0, s1
	s_ashr_i32 s6, s1, 7
	s_and_b32 s1, s1, 0xff80
	s_sub_i32 s0, s0, s1
	s_bfe_i32 s1, s0, 0x80000
	s_bfe_u32 s1, s1, 0x3000c
	s_add_i32 s1, s0, s1
	s_bfe_i32 s7, s1, 0x80000
	s_and_b32 s1, s1, 0xf8
	s_sub_i32 s0, s0, s1
	s_lshl_b32 s6, s6, 3
	s_sext_i32_i16 s7, s7
	s_sext_i32_i8 s0, s0
	s_add_i32 s34, s6, s0
	s_ashr_i32 s30, s7, 3
	s_lshr_b32 s0, s30, 2
	s_and_b32 s1, s34, 7
	s_and_b32 s6, s30, 3
	s_and_b32 s34, s34, -8
	s_lshr_b32 s30, s0, 1
	s_lshl_b32 s30, s30, 2
	s_add_i32 s34, s34, s30
	s_and_b32 s30, s1, 3
	s_add_i32 s34, s34, s30
	s_and_b32 s0, s0, 1
	s_lshl_b32 s0, s0, 3
	s_lshl_b32 s6, s6, 1
	s_lshr_b32 s1, s1, 2
	s_add_i32 s30, s0, s6
	s_add_i32 s30, s30, s1

;     __host__ __device__ bool next(int i, Unit& u) const {
;     ...
;         int wgid = (int)L; { const int q = nwg / NXCD, r = nwg % NXCD, xcd = wgid % NXCD, off = wgid / NXCD; wgid = (xcd < r ? xcd * (q + 1) : r * (q + 1) + (xcd - r) * q) + off; }
;         const int nig = WGM * nN, gid = wgid / nig, fm = gid * WGM, gsz = (nM - fm) < WGM ? (nM - fm) : WGM;
;         u.pm = fm + ((wgid % nig) % gsz); u.pn = (wgid % nig) / gsz; return true;
.LBB0_1087:
	s_ashr_i32 s22, s24, 3
	s_add_i32 s22, s26, s22
	s_ashr_i32 s23, s22, 31
	s_lshr_b32 s23, s23, 25
	s_add_i32 s23, s22, s23
	s_ashr_i32 s24, s23, 7
	s_lshl_b32 s24, s24, 3
	s_sub_i32 s25, 64, s24
	s_min_i32 s25, s25, 8
	s_abs_i32 s26, s25
	v_cvt_f32_u32_e32 v2, s26
	s_sub_i32 s28, 0, s26
	s_and_b32 s23, s23, 0xffffff80
	s_sub_i32 s23, s22, s23
	v_rcp_iflag_f32_e32 v2, v2
	s_abs_i32 s22, s23
	s_xor_b32 s27, s23, s25
	s_ashr_i32 s27, s27, 31
	v_mul_f32_e32 v2, 0x4f7ffffe, v2
	v_cvt_u32_f32_e32 v2, v2
	s_nop 0
	v_readfirstlane_b32 s29, v2
	s_mul_i32 s28, s28, s29
	s_mul_hi_u32 s28, s29, s28
	s_add_i32 s29, s29, s28
	s_mul_hi_u32 s28, s22, s29
	s_mul_i32 s29, s28, s26
	s_sub_i32 s22, s22, s29
	s_add_i32 s31, s28, 1
	s_sub_i32 s29, s22, s26
	s_cmp_ge_u32 s22, s26
	s_cselect_b32 s28, s31, s28
	s_cselect_b32 s22, s29, s22
	s_add_i32 s29, s28, 1
	s_cmp_ge_u32 s22, s26
	s_cselect_b32 s22, s29, s28
	s_xor_b32 s22, s22, s27
	s_sub_i32 s22, s22, s27
	s_mul_i32 s25, s22, s25
	s_sub_i32 s23, s23, s25
	s_add_i32 s24, s24, s23
	s_lshr_b32 s25, s22, 2
	s_and_b32 s26, s24, 7
	s_and_b32 s27, s22, 3
	s_and_b32 s24, s24, -8
	s_lshr_b32 s22, s25, 1
	s_lshl_b32 s22, s22, 2
	s_add_i32 s24, s24, s22
	s_and_b32 s22, s26, 3
	s_add_i32 s24, s24, s22
	s_and_b32 s25, s25, 1
	s_lshl_b32 s25, s25, 3
	s_lshl_b32 s27, s27, 1
	s_lshr_b32 s26, s26, 2
	s_add_i32 s22, s25, s27
	s_add_i32 s22, s22, s26
